# grid barrier: non-leader workgroups poll the cross-XCD release word directly (no per-XCD relay hop), on top of the early L1 invalidate
# speedup vs baseline: 1.0221x; 1.0073x over previous
.LBB0_90:
	v_readlane_b32 s4, v254, 5
	s_lshl_b32 s4, s4, 8
	v_readlane_b32 s6, v254, 3
	v_readlane_b32 s7, v254, 4
	s_add_u32 s4, s6, s4
	s_addc_u32 s5, s7, 0
	v_mov_b32_e32 v1, 0x1000
	v_mov_b32_e32 v3, 1
	global_atomic_add v3, v1, v3, s[4:5] offset:1024 sc0
	buffer_inv sc1
	v_cvt_f32_u32_e32 v1, v2
	v_sub_u32_e32 v4, 0, v2
	v_rcp_iflag_f32_e32 v1, v1
	s_nop 0
	v_mul_f32_e32 v1, 0x4f7ffffe, v1
	v_cvt_u32_f32_e32 v1, v1
	v_mul_lo_u32 v4, v4, v1
	v_mul_hi_u32 v4, v1, v4
	v_add_u32_e32 v1, v1, v4
	s_waitcnt vmcnt(1)
	v_mul_hi_u32 v1, v3, v1
	v_mul_lo_u32 v4, v1, v2
	v_sub_u32_e32 v4, v3, v4
	v_add_u32_e32 v5, 1, v1
	v_cmp_ge_u32_e32 vcc, v4, v2
	v_add_u32_e32 v3, 1, v3
	s_nop 0
	v_cndmask_b32_e32 v1, v1, v5, vcc
	v_sub_u32_e32 v5, v4, v2
	v_cndmask_b32_e32 v4, v4, v5, vcc
	v_add_u32_e32 v5, 1, v1
	v_cmp_ge_u32_e32 vcc, v4, v2
	s_nop 1
	v_cndmask_b32_e32 v1, v1, v5, vcc
	v_mul_lo_u32 v4, v2, v1
	v_add_u32_e32 v2, v4, v2
	v_cmp_ne_u32_e32 vcc, v3, v2
	s_and_saveexec_b64 s[6:7], vcc
	s_xor_b64 s[6:7], exec, s[6:7]
	s_cbranch_execz .LBB0_104
	s_waitcnt lgkmcnt(0)
	s_add_u32 s12, s28, 0x7500
	s_addc_u32 s13, s29, 0
	v_mov_b32_e32 v0, 0
	global_load_dword v0, v0, s[12:13] sc1
	s_waitcnt vmcnt(0)
	v_cmp_eq_u32_e32 vcc, v0, v1
	s_and_saveexec_b64 s[8:9], vcc
	s_cbranch_execz .LBB0_103
	s_add_u32 s10, s28, 0x4200
	s_addc_u32 s11, s29, 0
	s_mov_b32 s56, 1
	s_mov_b64 s[14:15], 0
	v_mov_b32_e32 v0, 0
	s_branch .LBB0_94

.LBB0_312:
	v_readlane_b32 s4, v254, 5
	s_lshl_b32 s4, s4, 8
	v_readlane_b32 s6, v254, 3
	v_readlane_b32 s7, v254, 4
	s_add_u32 s4, s6, s4
	s_addc_u32 s5, s7, 0
	v_mov_b32_e32 v1, 0x1000
	v_mov_b32_e32 v3, 1
	global_atomic_add v3, v1, v3, s[4:5] offset:1024 sc0
	buffer_inv sc1
	v_cvt_f32_u32_e32 v1, v2
	v_sub_u32_e32 v4, 0, v2
	v_rcp_iflag_f32_e32 v1, v1
	s_nop 0
	v_mul_f32_e32 v1, 0x4f7ffffe, v1
	v_cvt_u32_f32_e32 v1, v1
	v_mul_lo_u32 v4, v4, v1
	v_mul_hi_u32 v4, v1, v4
	v_add_u32_e32 v1, v1, v4
	s_waitcnt vmcnt(1)
	v_mul_hi_u32 v1, v3, v1
	v_mul_lo_u32 v4, v1, v2
	v_sub_u32_e32 v4, v3, v4
	v_add_u32_e32 v5, 1, v1
	v_cmp_ge_u32_e32 vcc, v4, v2
	v_add_u32_e32 v3, 1, v3
	s_nop 0
	v_cndmask_b32_e32 v1, v1, v5, vcc
	v_sub_u32_e32 v5, v4, v2
	v_cndmask_b32_e32 v4, v4, v5, vcc
	v_add_u32_e32 v5, 1, v1
	v_cmp_ge_u32_e32 vcc, v4, v2
	s_nop 1
	v_cndmask_b32_e32 v1, v1, v5, vcc
	v_mul_lo_u32 v4, v2, v1
	v_add_u32_e32 v2, v4, v2
	v_cmp_ne_u32_e32 vcc, v3, v2
	s_and_saveexec_b64 s[6:7], vcc
	s_xor_b64 s[6:7], exec, s[6:7]
	s_cbranch_execz .LBB0_326
	s_waitcnt lgkmcnt(0)
	s_add_u32 s12, s28, 0x7500
	s_addc_u32 s13, s29, 0
	v_mov_b32_e32 v0, 0
	global_load_dword v0, v0, s[12:13] sc1
	s_waitcnt vmcnt(0)
	v_cmp_eq_u32_e32 vcc, v0, v1
	s_and_saveexec_b64 s[8:9], vcc
	s_cbranch_execz .LBB0_325
	s_add_u32 s10, s28, 0x4200
	s_addc_u32 s11, s29, 0
	s_mov_b32 s40, 1
	s_mov_b64 s[14:15], 0
	v_mov_b32_e32 v0, 0
	s_branch .LBB0_316

.LBB0_1117:
	v_readlane_b32 s4, v254, 5
	s_lshl_b32 s4, s4, 8
	v_readlane_b32 s6, v254, 3
	v_readlane_b32 s7, v254, 4
	s_add_u32 s4, s6, s4
	s_addc_u32 s5, s7, 0
	v_mov_b32_e32 v1, 0x1000
	v_mov_b32_e32 v3, 1
	global_atomic_add v3, v1, v3, s[4:5] offset:1024 sc0
	buffer_inv sc1
	v_cvt_f32_u32_e32 v1, v2
	v_sub_u32_e32 v4, 0, v2
	v_rcp_iflag_f32_e32 v1, v1
	s_nop 0
	v_mul_f32_e32 v1, 0x4f7ffffe, v1
	v_cvt_u32_f32_e32 v1, v1
	v_mul_lo_u32 v4, v4, v1
	v_mul_hi_u32 v4, v1, v4
	v_add_u32_e32 v1, v1, v4
	s_waitcnt vmcnt(1)
	v_mul_hi_u32 v1, v3, v1
	v_mul_lo_u32 v4, v1, v2
	v_sub_u32_e32 v4, v3, v4
	v_add_u32_e32 v5, 1, v1
	v_cmp_ge_u32_e32 vcc, v4, v2
	v_add_u32_e32 v3, 1, v3
	s_nop 0
	v_cndmask_b32_e32 v1, v1, v5, vcc
	v_sub_u32_e32 v5, v4, v2
	v_cndmask_b32_e32 v4, v4, v5, vcc
	v_add_u32_e32 v5, 1, v1
	v_cmp_ge_u32_e32 vcc, v4, v2
	s_nop 1
	v_cndmask_b32_e32 v1, v1, v5, vcc
	v_mul_lo_u32 v4, v2, v1
	v_add_u32_e32 v2, v4, v2
	v_cmp_ne_u32_e32 vcc, v3, v2
	s_and_saveexec_b64 s[6:7], vcc
	s_xor_b64 s[6:7], exec, s[6:7]
	s_cbranch_execz .LBB0_1131
	s_waitcnt lgkmcnt(0)
	s_add_u32 s14, s28, 0x7500
	s_addc_u32 s15, s29, 0
	v_mov_b32_e32 v0, 0
	global_load_dword v0, v0, s[14:15] sc1
	s_waitcnt vmcnt(0)
	v_cmp_eq_u32_e32 vcc, v0, v1
	s_and_saveexec_b64 s[10:11], vcc
	s_cbranch_execz .LBB0_1130
	s_add_u32 s12, s28, 0x4200
	s_addc_u32 s13, s29, 0
	s_mov_b32 s40, 1
	s_mov_b64 s[18:19], 0
	v_mov_b32_e32 v0, 0
	s_branch .LBB0_1121

.LBB0_1825:
	v_readlane_b32 s4, v254, 5
	s_lshl_b32 s4, s4, 8
	v_readlane_b32 s6, v254, 3
	v_readlane_b32 s7, v254, 4
	s_add_u32 s4, s6, s4
	s_addc_u32 s5, s7, 0
	v_mov_b32_e32 v1, 0x1000
	v_mov_b32_e32 v3, 1
	global_atomic_add v3, v1, v3, s[4:5] offset:1024 sc0
	buffer_inv sc1
	v_cvt_f32_u32_e32 v1, v2
	v_sub_u32_e32 v4, 0, v2
	v_rcp_iflag_f32_e32 v1, v1
	s_nop 0
	v_mul_f32_e32 v1, 0x4f7ffffe, v1
	v_cvt_u32_f32_e32 v1, v1
	v_mul_lo_u32 v4, v4, v1
	v_mul_hi_u32 v4, v1, v4
	v_add_u32_e32 v1, v1, v4
	s_waitcnt vmcnt(1)
	v_mul_hi_u32 v1, v3, v1
	v_mul_lo_u32 v4, v1, v2
	v_sub_u32_e32 v4, v3, v4
	v_add_u32_e32 v5, 1, v1
	v_cmp_ge_u32_e32 vcc, v4, v2
	v_add_u32_e32 v3, 1, v3
	s_nop 0
	v_cndmask_b32_e32 v1, v1, v5, vcc
	v_sub_u32_e32 v5, v4, v2
	v_cndmask_b32_e32 v4, v4, v5, vcc
	v_add_u32_e32 v5, 1, v1
	v_cmp_ge_u32_e32 vcc, v4, v2
	s_nop 1
	v_cndmask_b32_e32 v1, v1, v5, vcc
	v_mul_lo_u32 v4, v2, v1
	v_add_u32_e32 v2, v4, v2
	v_cmp_ne_u32_e32 vcc, v3, v2
	s_and_saveexec_b64 s[6:7], vcc
	s_xor_b64 s[6:7], exec, s[6:7]
	s_cbranch_execz .LBB0_1839
	s_waitcnt lgkmcnt(0)
	s_add_u32 s12, s28, 0x7500
	s_addc_u32 s13, s29, 0
	v_mov_b32_e32 v0, 0
	global_load_dword v0, v0, s[12:13] sc1
	s_waitcnt vmcnt(0)
	v_cmp_eq_u32_e32 vcc, v0, v1
	s_and_saveexec_b64 s[8:9], vcc
	s_cbranch_execz .LBB0_1838
	s_add_u32 s10, s28, 0x4200
	s_addc_u32 s11, s29, 0
	s_mov_b32 s31, 1
	s_mov_b64 s[14:15], 0
	v_mov_b32_e32 v0, 0
	s_branch .LBB0_1829
